# v7 plus static s_setprio 2 for waves 0-3 during the attention phase
# baseline (speedup 1.0000x reference)
; #define LAS __attribute__((address_space(3)))
; template <class T> __device__ __forceinline__ T* launder(T* p) { asm volatile("" : "+s"(p)); return p; }
; #define PH_IDS() const int tid = opaque_tid(), lane = tid & 63, wave = __builtin_amdgcn_readfirstlane(tid >> 6), r32 = lane & 31, hi = lane >> 5; \
;     const int G = gridDim.x, gw = blockIdx.x * 8 + wave, ngw = G * 8; (void)r32; (void)hi; (void)gw; (void)ngw; (void)G
; #define INP(T, k) ((const T*)launder(a.in[k]))
; __device__ __forceinline__ void ph_attn(const Args& a, char* lds, int l, int rep) {
;     PH_IDS(); unsigned char* ws = launder(a.ws);
;     const bf16_t* P = WSP(bf16_t, WS_P); bf16_t* MIX = WSP(bf16_t, WS_MIX);
;     volatile LAS unsigned* ldsctl = (volatile LAS unsigned*)((LAS char*)lds + LDSCTL_OFF);
;     const float lam_init = 0.8f - 0.6f * expf(-0.3f * (float)l);
;     const float* lq1 = INP(float, 14); const float* lk1 = INP(float, 15); const float* lq2 = INP(float, 16); const float* lk2 = INP(float, 17);
;     float d1 = 0.f, d2 = 0.f;
;     for (int i = 0; i < 64; ++i) { d1 += lq1[l * 64 + i] * lk1[l * 64 + i]; d2 += lq2[l * 64 + i] * lk2[l * 64 + i]; }
;     const float lam = expf(d1) - expf(d2) + lam_init;
;     unsigned* ctr = WSP(unsigned, WS_CTL) + 64 * (1 + l + 8 * rep);
.LBB0_857:
	s_add_u32 s14, s2, s4
	s_addc_u32 s15, s6, s5
	v_mov_b64_e32 v[20:21], s[14:15]
	s_add_u32 s14, s7, s4
	s_addc_u32 s15, s8, s5
	v_mov_b64_e32 v[22:23], s[14:15]
	s_add_u32 s14, s9, s4
	s_addc_u32 s15, s10, s5
	v_mov_b64_e32 v[24:25], s[14:15]
	s_add_u32 s14, s11, s4
	s_addc_u32 s15, s12, s5
	v_mov_b64_e32 v[26:27], s[14:15]
	flat_load_dwordx4 v[4:7], v[20:21]
	flat_load_dwordx4 v[8:11], v[22:23]
	flat_load_dwordx4 v[12:15], v[24:25]
	flat_load_dwordx4 v[16:19], v[26:27]
	s_add_u32 s4, s4, 32
	s_addc_u32 s5, s5, 0
	s_cmpk_eq_i32 s4, 0x100
	s_waitcnt vmcnt(0) lgkmcnt(0)
	v_mov_b32_e32 v28, v4
	v_mov_b32_e32 v30, v8
	v_mov_b32_e32 v29, v12
	v_mov_b32_e32 v31, v16
	v_pk_fma_f32 v[2:3], v[28:29], v[30:31], v[2:3]
	v_mov_b32_e32 v12, v5
	v_mov_b32_e32 v16, v9
	v_pk_fma_f32 v[2:3], v[12:13], v[16:17], v[2:3]
	v_mov_b32_e32 v4, v6
	v_mov_b32_e32 v5, v14
	v_mov_b32_e32 v8, v10
	v_mov_b32_e32 v9, v18
	v_pk_fma_f32 v[2:3], v[4:5], v[8:9], v[2:3]
	v_mov_b32_e32 v14, v7
	v_mov_b32_e32 v18, v11
	v_pk_fma_f32 v[18:19], v[14:15], v[18:19], v[2:3]
	flat_load_dwordx4 v[2:5], v[20:21] offset:16
	flat_load_dwordx4 v[6:9], v[22:23] offset:16
	flat_load_dwordx4 v[10:13], v[24:25] offset:16
	flat_load_dwordx4 v[14:17], v[26:27] offset:16
	s_waitcnt vmcnt(0) lgkmcnt(0)
	v_mov_b32_e32 v20, v2
	v_mov_b32_e32 v22, v6
	v_mov_b32_e32 v21, v10
	v_mov_b32_e32 v23, v14
	v_pk_fma_f32 v[18:19], v[20:21], v[22:23], v[18:19]
	v_mov_b32_e32 v10, v3
	v_mov_b32_e32 v14, v7
	v_pk_fma_f32 v[2:3], v[10:11], v[14:15], v[18:19]
	v_mov_b32_e32 v6, v4
	v_mov_b32_e32 v7, v12
	v_mov_b32_e32 v10, v8
	v_mov_b32_e32 v11, v16
	v_pk_fma_f32 v[2:3], v[6:7], v[10:11], v[2:3]
	v_mov_b32_e32 v12, v5
	v_mov_b32_e32 v16, v9
	v_pk_fma_f32 v[2:3], v[12:13], v[16:17], v[2:3]
	s_cbranch_scc0 .LBB0_857
	v_cvt_f32_u32_e32 v4, s66
	s_mov_b32 s4, 0x3fb8aa3b
	s_mov_b32 s5, 0xc2ce8ed0
	s_mov_b32 s6, 0x42b17218
	v_mul_f32_e32 v4, 0xbe99999a, v4
	v_mul_f32_e32 v5, 0x3fb8aa3b, v4
	v_fma_f32 v6, v4, s4, -v5
	v_rndne_f32_e32 v7, v5
	v_fmac_f32_e32 v6, 0x32a5705f, v4
	v_sub_f32_e32 v5, v5, v7
	v_add_f32_e32 v5, v5, v6
	v_exp_f32_e32 v5, v5
	v_cvt_i32_f32_e32 v6, v7
	v_cmp_ngt_f32_e32 vcc, s5, v4
	v_mov_b32_e32 v8, 0x7f800000
	s_lshl_b32 s86, s66, 6
	v_ldexp_f32 v5, v5, v6
	v_cndmask_b32_e32 v5, 0, v5, vcc
	v_cmp_nlt_f32_e32 vcc, s6, v4
	s_add_u32 s7, s0, 0x1d9c0000
	v_writelane_b32 v255, s7, 36
	v_cndmask_b32_e32 v4, v8, v5, vcc
	v_mov_b32_e32 v5, 0x3f4ccccd
	v_fmamk_f32 v4, v4, 0xbf19999a, v5
	v_mul_f32_e32 v5, 0x3fb8aa3b, v2
	v_rndne_f32_e32 v6, v5
	v_sub_f32_e32 v7, v5, v6
	v_fma_f32 v5, v2, s4, -v5
	v_fmac_f32_e32 v5, 0x32a5705f, v2
	v_add_f32_e32 v5, v7, v5
	v_exp_f32_e32 v5, v5
	v_cvt_i32_f32_e32 v6, v6
	v_cmp_ngt_f32_e32 vcc, s5, v2
	s_addc_u32 s7, s1, 0
	v_writelane_b32 v255, s7, 37
	v_ldexp_f32 v5, v5, v6
	v_cndmask_b32_e32 v5, 0, v5, vcc
	v_cmp_nlt_f32_e32 vcc, s6, v2
	s_add_u32 s7, s0, 0x271c0000
	v_writelane_b32 v255, s7, 38
	v_cndmask_b32_e32 v2, v8, v5, vcc
	v_mul_f32_e32 v5, 0x3fb8aa3b, v3
	v_rndne_f32_e32 v6, v5
	s_addc_u32 s7, s1, 0
	v_sub_f32_e32 v7, v5, v6
	v_fma_f32 v5, v3, s4, -v5
	v_cmp_ngt_f32_e32 vcc, s5, v3
	s_lshl_b64 s[4:5], s[86:87], 2
	s_add_u32 s4, s0, s4
	v_writelane_b32 v255, s7, 39
	s_addc_u32 s5, s1, s5
	v_readfirstlane_b32 s2, v0
	v_writelane_b32 v255, s4, 40
	v_fmac_f32_e32 v5, 0x32a5705f, v3
	s_ashr_i32 s2, s2, 1
	v_writelane_b32 v255, s5, 41
	v_cmp_eq_u32_e64 s[4:5], 0, v0
	v_add_f32_e32 v5, v7, v5
	s_andn2_b32 s2, s2, 31
	v_writelane_b32 v255, s4, 42
	v_exp_f32_e32 v5, v5
	v_cvt_i32_f32_e32 v6, v6
	v_writelane_b32 v255, s5, 43
	s_ashr_i32 s4, s2, 31
	v_writelane_b32 v255, s4, 44
	s_add_u32 s4, s0, 0x2b1c0000
	v_writelane_b32 v255, s4, 45
	s_addc_u32 s4, s1, 0
	v_writelane_b32 v255, s4, 46
	s_add_u32 s4, s0, 0x2c9c0000
	v_ldexp_f32 v5, v5, v6
	v_writelane_b32 v255, s4, 47
	s_addc_u32 s4, s1, 0
	v_cndmask_b32_e32 v5, 0, v5, vcc
	v_cmp_nlt_f32_e32 vcc, s6, v3
	v_writelane_b32 v255, s4, 48
	s_add_u32 s0, s0, 0x32200000
	v_cndmask_b32_e32 v3, v8, v5, vcc
	v_writelane_b32 v255, s0, 49
	s_addc_u32 s0, s1, 0
	v_sub_f32_e32 v2, v2, v3
	v_writelane_b32 v255, s0, 50
	v_and_b32_e32 v146, 31, v0
	v_add_f32_e32 v147, v4, v2
	v_lshlrev_b32_e32 v2, 8, v0
	v_and_b32_e32 v0, 1, v0
	v_writelane_b32 v255, s2, 51
	s_add_i32 s0, s2, 0x700
	v_and_b32_e32 v148, 0x2000, v2
	v_cmp_eq_u32_e64 s[8:9], 0, v0
	v_lshl_or_b32 v150, s66, 7, v146
	v_sub_f32_e32 v149, 1.0, v4
	v_mov_b32_e32 v151, v1
	v_writelane_b32 v255, s0, 52
	s_cmpk_lt_u32 s2, 0x80
	s_cbranch_scc0 .Lprio_skip
	s_setprio 2
.Lprio_skip:
	s_branch .LBB0_862
.LBB0_859:
	s_or_b64 exec, exec, s[0:1]

; __device__ __forceinline__ unsigned xb_ld(unsigned* p)              { return __hip_atomic_load(p, __ATOMIC_RELAXED, __HIP_MEMORY_SCOPE_AGENT); }
; __device__ __forceinline__ void xcd_barrier_complete(unsigned* bar, unsigned x, unsigned& nloc, unsigned& nx) {
;     const unsigned G = gridDim.x * gridDim.y * gridDim.z;
;     unsigned sum, cnt, mine, sp = 0u;
;     for (;;) {
;         sum = 0u; cnt = 0u; mine = 0u;
; #pragma unroll
;         for (unsigned j = 0; j < 16; ++j) { const unsigned c = xb_ld(&bar[XB_XCNT(j)]); sum += c; cnt += (c > 0u) ? 1u : 0u; mine = (j == x) ? c : mine; }
; __device__ __forceinline__ void xcd_barrier(const XcdBarrier& b) {
;     asm volatile("s_waitcnt vmcnt(0)" ::: "memory");
;     __syncthreads();
;     if (threadIdx.x == 0) {
;         unsigned* bar = b.bar;
;         __builtin_amdgcn_s_waitcnt(0);
;         unsigned nloc = b.st[0], nx = b.st[1];
;         if (nloc == 0u) { xcd_barrier_complete(bar, b.x, nloc, nx); b.st[0] = nloc; b.st[1] = nx; }
.LBB0_1327:
	s_setprio 0
	s_mov_b64 s[4:5], s[76:77]
	s_mov_b32 s62, s87
	s_getreg_b32 s2, hwreg(HW_REG_XCC_ID, 0, 4)
	s_waitcnt vmcnt(0)
	s_waitcnt vmcnt(0) lgkmcnt(0)
	s_barrier
	s_mov_b64 s[0:1], exec
	v_readlane_b32 s6, v253, 16
	v_readlane_b32 s7, v253, 17
	s_and_b64 s[6:7], s[0:1], s[6:7]
	s_mov_b64 exec, s[6:7]
	s_cbranch_execz .LBB0_1371
	s_add_i32 s43, s62, 0x20020
	v_mov_b32_e32 v0, s43
	s_waitcnt vmcnt(0) expcnt(0) lgkmcnt(0)
	ds_read_b32 v2, v0
	s_add_i32 s62, s62, 0x20024
	v_mov_b32_e32 v0, s62
	ds_read_b32 v0, v0
	s_and_b32 s2, s2, 15
	s_waitcnt lgkmcnt(1)
	v_cmp_ne_u32_e32 vcc, 0, v2
	s_cbranch_vccnz .LBB0_1342
	s_add_u32 s6, s4, 0x4200
	s_addc_u32 s7, s5, 0
	s_add_u32 s8, s4, 0x4400
	s_addc_u32 s9, s5, 0
	s_add_u32 s10, s4, 0x4500
	s_addc_u32 s11, s5, 0
	s_add_u32 s12, s4, 0x4600
	s_addc_u32 s13, s5, 0
	s_add_u32 s14, s4, 0x4700
	s_addc_u32 s15, s5, 0
	s_add_u32 s16, s4, 0x4800
	s_addc_u32 s17, s5, 0
	s_add_u32 s18, s4, 0x4900
	s_addc_u32 s19, s5, 0
	s_add_u32 s20, s4, 0x4a00
	s_addc_u32 s21, s5, 0
	s_add_u32 s22, s4, 0x4b00
	s_addc_u32 s23, s5, 0
	s_add_u32 s24, s4, 0x4c00
	s_addc_u32 s25, s5, 0
	s_add_u32 s26, s4, 0x4d00
	s_addc_u32 s27, s5, 0
	s_add_u32 s28, s4, 0x4e00
	s_addc_u32 s29, s5, 0
	s_add_u32 s30, s4, 0x4f00
	s_addc_u32 s31, s5, 0
	s_add_u32 s34, s4, 0x5000
	s_addc_u32 s35, s5, 0
	s_add_u32 s36, s4, 0x5100
	s_addc_u32 s37, s5, 0
	s_add_u32 s38, s4, 0x5200
	s_addc_u32 s39, s5, 0
	s_add_u32 s40, s4, 0x5300
	s_addc_u32 s41, s5, 0
	s_mov_b32 s63, 1
	s_mov_b64 s[44:45], 0
	s_branch .LBB0_1332
